# v56 + scan A1/A2 cross-row reductions (xor 16, xor 32) via v_permlane16_swap / v_permlane32_swap on a register copy instead of two dependent ds_bpermute round trips
# speedup vs baseline: 1.0074x; 1.0054x over previous
.LBB0_538:
	s_sub_i32 s22, s28, s29
	s_min_u32 s24, s22, 64
	s_lshr_b32 s22, s24, 4
	s_cmp_lt_u32 s68, s22
	s_cselect_b64 s[34:35], -1, 0
	s_cmp_ge_u32 s68, s22
	s_cbranch_scc1 .LBB0_542
	ds_read_b64 v[24:25], v207
	ds_read_b64 v[34:35], v132
	ds_read_b64 v[8:9], v208
	ds_read_b64 v[26:27], v209
	ds_read_b64 v[36:37], v210
	ds_read2_b64 v[20:23], v135 offset1:32
	ds_read_b64 v[38:39], v134
	ds_read_b64 v[28:29], v136
	ds_read_b64 v[40:41], v211
	ds_read_b64 v[42:43], v131
	ds_read_b64 v[32:33], v212
	s_waitcnt lgkmcnt(7)
	v_pk_add_f16 v11, v26, v24 neg_lo:[0,1] neg_hi:[0,1]
	v_pk_add_f16 v26, v27, v25 neg_lo:[0,1] neg_hi:[0,1]
	s_waitcnt lgkmcnt(3)
	v_pk_fma_f16 v66, v11, v28, v24
	v_pk_fma_f16 v67, v26, v29, v25
	ds_read_b64 v[68:69], v133
	ds_read2_b64 v[28:31], v135 offset0:96 offset1:112
	s_waitcnt lgkmcnt(4)
	v_pk_add_f16 v11, v36, v40 neg_lo:[0,1] neg_hi:[0,1]
	v_pk_add_f16 v70, v37, v41 neg_lo:[0,1] neg_hi:[0,1]
	v_pk_add_f16 v38, v38, v34 neg_lo:[0,1] neg_hi:[0,1]
	s_waitcnt lgkmcnt(1)
	v_pk_add_f16 v24, v68, v42 neg_lo:[0,1] neg_hi:[0,1]
	v_pk_add_f16 v25, v69, v43 neg_lo:[0,1] neg_hi:[0,1]
	s_waitcnt lgkmcnt(0)
	v_pk_fma_f16 v24, v24, v28, v42
	v_pk_fma_f16 v25, v25, v29, v43
	v_fma_mix_f32 v36, v24, s86, 0 op_sel_hi:[1,0,0]
	v_fma_mix_f32 v43, v24, s86, 0 op_sel:[1,0,0] op_sel_hi:[1,0,0]
	v_fma_mix_f32 v37, v25, s86, 0 op_sel_hi:[1,0,0]
	v_fma_mix_f32 v42, v25, s86, 0 op_sel:[1,0,0] op_sel_hi:[1,0,0]
	ds_read2_b64 v[24:27], v135 offset0:64 offset1:80
	v_exp_f32_e32 v36, v36
	v_exp_f32_e32 v43, v43
	v_exp_f32_e32 v37, v37
	v_exp_f32_e32 v42, v42
	v_add_f32_e32 v28, 1.0, v36
	v_add_f32_e32 v36, 1.0, v43
	v_rcp_f32_e32 v28, v28
	v_rcp_f32_e32 v29, v36
	s_waitcnt lgkmcnt(0)
	v_pk_mul_f16 v69, v67, v25
	v_add_f32_e32 v36, 1.0, v37
	v_add_f32_e32 v37, 1.0, v42
	v_rcp_f32_e32 v36, v36
	v_rcp_f32_e32 v37, v37
	v_pk_mul_f16 v68, v66, v24
	v_pk_fma_f32 v[24:25], v[28:29], -2.0, 1.0 op_sel_hi:[1,0,0]
	v_pk_add_f16 v39, v39, v35 neg_lo:[0,1] neg_hi:[0,1]
	v_pk_fma_f32 v[28:29], v[36:37], -2.0, 1.0 op_sel_hi:[1,0,0]
	v_pk_fma_f16 v31, v39, v31, v35
	v_cvt_pk_f16_f32 v29, v28, v29
	v_cvt_pk_f16_f32 v28, v24, v25
	v_pk_fma_f16 v30, v38, v30, v34
	ds_write_b64 v109, v[28:29] offset:56320
	v_pk_fma_f16 v23, v70, v23, v41
	v_pk_fma_f16 v22, v11, v22, v40
	ds_write_b64 v213, v[30:31]
	ds_write_b64 v214, v[22:23] offset:9216
	ds_read_b64 v[28:29], v215
	ds_read_b64 v[42:43], v138
	ds_read_b64 v[34:35], v216
	ds_read_b64 v[30:31], v217
	ds_read_b64 v[72:73], v218
	ds_read2_b64 v[22:25], v141 offset1:32
	ds_read_b64 v[74:75], v140
	ds_read_b64 v[38:39], v142
	ds_read_b64 v[76:77], v219
	ds_read_b64 v[78:79], v137
	s_waitcnt lgkmcnt(12)
	ds_read_b64 v[36:37], v220
	s_waitcnt lgkmcnt(7)
	v_pk_add_f16 v30, v30, v28 neg_lo:[0,1] neg_hi:[0,1]
	v_pk_add_f16 v31, v31, v29 neg_lo:[0,1] neg_hi:[0,1]
	s_waitcnt lgkmcnt(3)
	v_pk_fma_f16 v70, v30, v38, v28
	v_pk_fma_f16 v71, v31, v39, v29
	ds_read_b64 v[80:81], v139
	ds_read2_b64 v[38:41], v141 offset0:96 offset1:112
	s_waitcnt lgkmcnt(4)
	v_pk_add_f16 v82, v72, v76 neg_lo:[0,1] neg_hi:[0,1]
	v_pk_add_f16 v83, v73, v77 neg_lo:[0,1] neg_hi:[0,1]
	v_pk_add_f16 v84, v74, v42 neg_lo:[0,1] neg_hi:[0,1]
	s_waitcnt lgkmcnt(1)
	v_pk_add_f16 v85, v75, v43 neg_lo:[0,1] neg_hi:[0,1]
	v_pk_add_f16 v28, v80, v78 neg_lo:[0,1] neg_hi:[0,1]
	v_pk_add_f16 v29, v81, v79 neg_lo:[0,1] neg_hi:[0,1]
	s_waitcnt lgkmcnt(0)
	v_pk_fma_f16 v28, v28, v38, v78
	v_pk_fma_f16 v29, v29, v39, v79
	v_fma_mix_f32 v72, v28, s86, 0 op_sel_hi:[1,0,0]
	v_fma_mix_f32 v73, v28, s86, 0 op_sel:[1,0,0] op_sel_hi:[1,0,0]
	v_fma_mix_f32 v74, v29, s86, 0 op_sel_hi:[1,0,0]
	v_fma_mix_f32 v75, v29, s86, 0 op_sel:[1,0,0] op_sel_hi:[1,0,0]
	ds_read2_b64 v[28:31], v141 offset0:64 offset1:80
	v_exp_f32_e32 v72, v72
	v_exp_f32_e32 v73, v73
	v_exp_f32_e32 v74, v74
	v_exp_f32_e32 v75, v75
	v_add_f32_e32 v38, 1.0, v72
	v_add_f32_e32 v39, 1.0, v73
	v_add_f32_e32 v74, 1.0, v74
	v_add_f32_e32 v75, 1.0, v75
	v_rcp_f32_e32 v38, v38
	v_rcp_f32_e32 v39, v39
	v_rcp_f32_e32 v74, v74
	v_rcp_f32_e32 v75, v75
	v_mov_b32_e32 v11, v10
	s_waitcnt lgkmcnt(0)
	v_pk_mul_f16 v73, v71, v29
	v_pk_mul_f16 v72, v70, v28
	v_pk_fma_f32 v[28:29], v[38:39], -2.0, 1.0 op_sel_hi:[1,0,0]
	v_pk_fma_f32 v[38:39], v[74:75], -2.0, 1.0 op_sel_hi:[1,0,0]
	v_pk_fma_f16 v75, v83, v25, v77
	v_dot2c_f32_f16_e32 v11, v68, v68
	v_pk_fma_f16 v74, v82, v24, v76
	v_pk_fma_f16 v40, v84, v40, v42
	v_dot2c_f32_f16_e32 v11, v69, v69
	v_dot2c_f32_f16_e32 v11, v72, v72
	v_dot2c_f32_f16_e32 v11, v73, v73
	v_pk_fma_f16 v41, v85, v41, v43
	s_nop 1
	v_mov_b32_e32 v43, v11
	v_cvt_pk_f16_f32 v25, v38, v39
	v_cvt_pk_f16_f32 v24, v28, v29
	v_permlane16_swap_b32_e32 v11, v43
	ds_write_b64 v113, v[24:25] offset:56320
	ds_write_b64 v223, v[40:41]
	v_add_f32_e32 v11, v11, v43
	v_mov_b32_e32 v43, v11
	ds_write_b64 v224, v[74:75] offset:9216
	s_nop 1
	v_permlane32_swap_b32_e32 v11, v43
	s_nop 1
	s_and_saveexec_b64 s[22:23], s[0:1]
	s_cbranch_execz .LBB0_541
	v_add_f32_e32 v11, v11, v43
	v_add_u32_e32 v24, s80, v97
	ds_write_b32 v24, v11

.LBB0_570:
	s_or_b64 exec, exec, s[34:35]
	v_fma_mix_f32 v8, v76, v82, 0 op_sel_hi:[1,0,0]
	s_nop 0
	v_fma_mix_f32 v8, v76, v83, v8 op_sel:[1,0,0] op_sel_hi:[1,0,0]
	s_nop 0
	v_fma_mix_f32 v8, v77, v84, v8 op_sel_hi:[1,0,0]
	s_nop 0
	v_fma_mix_f32 v8, v77, v85, v8 op_sel:[1,0,0] op_sel_hi:[1,0,0]
	s_nop 0
	v_fma_mix_f32 v8, v80, v28, v8 op_sel_hi:[1,0,0]
	s_nop 0
	v_fma_mix_f32 v8, v80, v29, v8 op_sel:[1,0,0] op_sel_hi:[1,0,0]
	s_nop 0
	v_fma_mix_f32 v8, v81, v30, v8 op_sel_hi:[1,0,0]
	s_nop 0
	v_fma_mix_f32 v8, v81, v31, v8 op_sel:[1,0,0] op_sel_hi:[1,0,0]
	s_nop 0
	v_mov_b32_e32 v9, v8
	s_nop 1
	v_permlane16_swap_b32_e32 v8, v9
	s_nop 1
	v_add_f32_e32 v8, v8, v9
	v_mov_b32_e32 v9, v8
	s_nop 1
	v_permlane32_swap_b32_e32 v8, v9
	s_nop 1
	s_and_saveexec_b64 s[34:35], s[0:1]
	s_cbranch_execz .LBB0_572
	v_add_f32_e32 v8, v8, v9
	v_add_u32_e32 v9, s84, v97
	ds_write_b32 v9, v8
